# rmsnorm+modulate row loops (norm1, norm2): gain/scale/shift vectors of an iteration loaded up front (12 loads in flight) instead of a serialized 3-load round trip per output piece
# speedup vs baseline: 1.0107x; 1.0107x over previous
; DI void norm_phase(const float* lat, const float* ctxp, int nrows, const float* g, const float* modl, int shift_off, int scale_off,
;                    bf16_t* H, int bid, int nb) {
;     ...
;       const int row = r8 * 8 + wave + 4 * h;
;       const float* src = row < TL ? lat + (size_t)row * DM : ctxp + (size_t)(row - TL) * DM;
; #pragma unroll
;       for (int i = 0; i < 4; ++i) v[h][i] = *(const f32x4*)(src + lane * 4 + 256 * i);
;     }
; #pragma unroll
;     for (int h = 0; h < 2; ++h) {
; #pragma unroll
;       for (int i = 0; i < 4; ++i) ss[h] += v[h][i][0] * v[h][i][0] + v[h][i][1] * v[h][i][1] + v[h][i][2] * v[h][i][2] + v[h][i][3] * v[h][i][3];
;       ss[h] = wave_sum(ss[h]);
;     }
; #pragma unroll
;     for (int h = 0; h < 2; ++h) {
;       const int row = r8 * 8 + wave + 4 * h;
;       const int mi = row < TL ? (row >> 14) : 2;
;       const float* sh = modl + mi * 6144 + shift_off;
;       const float* sc = modl + mi * 6144 + scale_off;
;       const float rs = rsqrtf(ss[h] * (1.f / 1024.f) + EPS);
.LBB0_67:
	s_or_b64 exec, exec, s[2:3]
	v_lshl_add_u64 v[0:1], v[0:1], 0, v[38:39]
	global_load_dwordx4 v[16:19], v[0:1], off
	global_load_dwordx4 v[8:11], v[0:1], off offset:1024
	global_load_dwordx4 v[4:7], v[0:1], off offset:2048
	s_nop 0
	global_load_dwordx4 v[0:3], v[0:1], off offset:3072
	v_min_i32_e32 v168, 0x8000, v36
	v_readlane_b32 s24, v254, 46
	v_ashrrev_i32_e32 v168, 14, v168
	v_readlane_b32 s25, v254, 47
	v_mul_i32_i24_e32 v168, 0x1800, v168
	v_lshlrev_b64 v[182:183], 11, v[36:37]
	v_ashrrev_i32_e32 v169, 31, v168
	v_lshlrev_b64 v[184:185], 11, v[46:47]
	v_lshl_add_u64 v[170:171], v[168:169], 2, s[24:25]
	v_lshl_add_u64 v[172:173], v[170:171], 0, s[66:67]
	v_lshl_add_u64 v[170:171], v[170:171], 0, v[38:39]
	v_lshl_add_u64 v[172:173], v[172:173], 0, v[38:39]
	global_load_dwordx4 v[100:103], v[32:33], off
	global_load_dwordx4 v[116:119], v[172:173], off
	global_load_dwordx4 v[132:135], v[170:171], off
	global_load_dwordx4 v[104:107], v[32:33], off offset:1024
	global_load_dwordx4 v[120:123], v[172:173], off offset:1024
	global_load_dwordx4 v[136:139], v[170:171], off offset:1024
	global_load_dwordx4 v[108:111], v[32:33], off offset:2048
	global_load_dwordx4 v[124:127], v[172:173], off offset:2048
	global_load_dwordx4 v[140:143], v[170:171], off offset:2048
	global_load_dwordx4 v[112:115], v[32:33], off offset:3072
	global_load_dwordx4 v[128:131], v[172:173], off offset:3072
	global_load_dwordx4 v[164:167], v[170:171], off offset:3072
	v_lshl_add_u64 v[182:183], v[34:35], 0, v[182:183]
	v_lshl_add_u64 v[184:185], v[34:35], 0, v[184:185]
	s_waitcnt vmcnt(12)
	v_mul_f32_e32 v174, v28, v28
	v_fmac_f32_e32 v174, v29, v29
	v_fmac_f32_e32 v174, v30, v30
	v_fmac_f32_e32 v174, v31, v31
	v_fmac_f32_e32 v174, v24, v24
	v_fmac_f32_e32 v174, v25, v25
	v_fmac_f32_e32 v174, v26, v26
	v_fmac_f32_e32 v174, v27, v27
	v_fmac_f32_e32 v174, v20, v20
	v_fmac_f32_e32 v174, v21, v21
	v_fmac_f32_e32 v174, v22, v22
	v_fmac_f32_e32 v174, v23, v23
	v_fmac_f32_e32 v174, v12, v12
	v_fmac_f32_e32 v174, v13, v13
	v_fmac_f32_e32 v174, v14, v14
	v_fmac_f32_e32 v174, v15, v15
	v_mul_f32_e32 v175, v16, v16
	v_fmac_f32_e32 v175, v17, v17
	v_fmac_f32_e32 v175, v18, v18
	v_fmac_f32_e32 v175, v19, v19
	v_fmac_f32_e32 v175, v8, v8
	v_fmac_f32_e32 v175, v9, v9
	v_fmac_f32_e32 v175, v10, v10
	v_fmac_f32_e32 v175, v11, v11
	v_fmac_f32_e32 v175, v4, v4
	v_fmac_f32_e32 v175, v5, v5
	v_fmac_f32_e32 v175, v6, v6
	v_fmac_f32_e32 v175, v7, v7
	v_fmac_f32_e32 v175, v0, v0
	v_fmac_f32_e32 v175, v1, v1
	v_fmac_f32_e32 v175, v2, v2
	v_fmac_f32_e32 v175, v3, v3
	ds_bpermute_b32 v176, v48, v174
	ds_bpermute_b32 v177, v48, v175
	s_waitcnt lgkmcnt(0)
	v_add_f32_e32 v174, v174, v176
	v_add_f32_e32 v175, v175, v177
	ds_bpermute_b32 v176, v49, v174
	ds_bpermute_b32 v177, v49, v175
	s_waitcnt lgkmcnt(0)
	v_add_f32_e32 v174, v174, v176
	v_add_f32_e32 v175, v175, v177
	ds_bpermute_b32 v176, v50, v174
	ds_bpermute_b32 v177, v50, v175
	s_waitcnt lgkmcnt(0)
	v_add_f32_e32 v174, v174, v176
	v_add_f32_e32 v175, v175, v177
	ds_bpermute_b32 v176, v51, v174
	ds_bpermute_b32 v177, v51, v175
	s_waitcnt lgkmcnt(0)
	v_add_f32_e32 v174, v174, v176
	v_add_f32_e32 v175, v175, v177
	ds_bpermute_b32 v176, v52, v174
	ds_bpermute_b32 v177, v52, v175
	s_waitcnt lgkmcnt(0)
	v_add_f32_e32 v174, v174, v176
	v_add_f32_e32 v175, v175, v177
	ds_bpermute_b32 v176, v53, v174
	ds_bpermute_b32 v177, v53, v175
	s_waitcnt lgkmcnt(0)
	v_add_f32_e32 v174, v174, v176
	v_add_f32_e32 v175, v175, v177
	s_mov_b32 s2, 0x3a800000
	v_fma_f32 v174, v174, s2, v194
	v_fma_f32 v175, v175, s2, v194
	v_rsq_f32_e32 v178, v174
	v_rsq_f32_e32 v180, v175
	s_waitcnt vmcnt(0)
; DI unsigned pk2(float a, float b) { f32x2 v = {a, b}; return __builtin_bit_cast(unsigned, __builtin_convertvector(v, bf16x2_t)); }
; DI void norm_phase(const float* lat, const float* ctxp, int nrows, const float* g, const float* modl, int shift_off, int scale_off,
;                    bf16_t* H, int bid, int nb) {
;     ...
; #pragma unroll
;       for (int i = 0; i < 4; ++i) {
;         const int col = lane * 4 + 256 * i;
;         const f32x4 gg = *(const f32x4*)(g + col), s4 = *(const f32x4*)(sc + col), h4 = *(const f32x4*)(sh + col);
;         float y[4];
; #pragma unroll
;         for (int j = 0; j < 4; ++j) y[j] = (v[h][i][j] * rs * gg[j]) * (1.f + s4[j]) + h4[j];
;         u32x2 w; w[0] = pk2(y[0], y[1]); w[1] = pk2(y[2], y[3]);
;         *(u32x2*)(H + (size_t)row * DM + col) = w;
;       }
;     }
	v_pk_add_f32 v[116:117], v[116:117], 1.0 op_sel_hi:[1,0]
	v_pk_add_f32 v[118:119], v[118:119], 1.0 op_sel_hi:[1,0]
	v_pk_mul_f32 v[28:29], v[28:29], v[178:179] op_sel_hi:[1,0]
	v_pk_mul_f32 v[30:31], v[30:31], v[178:179] op_sel_hi:[1,0]
	v_pk_mul_f32 v[28:29], v[100:101], v[28:29]
	v_pk_mul_f32 v[30:31], v[102:103], v[30:31]
	v_pk_fma_f32 v[28:29], v[116:117], v[28:29], v[132:133]
	v_pk_fma_f32 v[30:31], v[118:119], v[30:31], v[134:135]
	v_cvt_pk_bf16_f32 v28, v28, v29
	v_cvt_pk_bf16_f32 v29, v30, v31
	global_store_dwordx2 v[182:183], v[28:29], off
	v_pk_mul_f32 v[16:17], v[16:17], v[180:181] op_sel_hi:[1,0]
	v_pk_mul_f32 v[18:19], v[18:19], v[180:181] op_sel_hi:[1,0]
	v_pk_mul_f32 v[16:17], v[100:101], v[16:17]
	v_pk_mul_f32 v[18:19], v[102:103], v[18:19]
	v_pk_fma_f32 v[16:17], v[116:117], v[16:17], v[132:133]
	v_pk_fma_f32 v[18:19], v[118:119], v[18:19], v[134:135]
	v_cvt_pk_bf16_f32 v16, v16, v17
	v_cvt_pk_bf16_f32 v17, v18, v19
	global_store_dwordx2 v[184:185], v[16:17], off
	v_pk_add_f32 v[120:121], v[120:121], 1.0 op_sel_hi:[1,0]
	v_pk_add_f32 v[122:123], v[122:123], 1.0 op_sel_hi:[1,0]
	v_pk_mul_f32 v[24:25], v[24:25], v[178:179] op_sel_hi:[1,0]
	v_pk_mul_f32 v[26:27], v[26:27], v[178:179] op_sel_hi:[1,0]
	v_pk_mul_f32 v[24:25], v[104:105], v[24:25]
	v_pk_mul_f32 v[26:27], v[106:107], v[26:27]
	v_pk_fma_f32 v[24:25], v[120:121], v[24:25], v[136:137]
	v_pk_fma_f32 v[26:27], v[122:123], v[26:27], v[138:139]
	v_cvt_pk_bf16_f32 v24, v24, v25
	v_cvt_pk_bf16_f32 v25, v26, v27
	global_store_dwordx2 v[182:183], v[24:25], off offset:512
	v_pk_mul_f32 v[8:9], v[8:9], v[180:181] op_sel_hi:[1,0]
	v_pk_mul_f32 v[10:11], v[10:11], v[180:181] op_sel_hi:[1,0]
	v_pk_mul_f32 v[8:9], v[104:105], v[8:9]
	v_pk_mul_f32 v[10:11], v[106:107], v[10:11]
	v_pk_fma_f32 v[8:9], v[120:121], v[8:9], v[136:137]
	v_pk_fma_f32 v[10:11], v[122:123], v[10:11], v[138:139]
	v_cvt_pk_bf16_f32 v8, v8, v9
	v_cvt_pk_bf16_f32 v9, v10, v11
	global_store_dwordx2 v[184:185], v[8:9], off offset:512
	v_pk_add_f32 v[124:125], v[124:125], 1.0 op_sel_hi:[1,0]
	v_pk_add_f32 v[126:127], v[126:127], 1.0 op_sel_hi:[1,0]
	v_pk_mul_f32 v[20:21], v[20:21], v[178:179] op_sel_hi:[1,0]
	v_pk_mul_f32 v[22:23], v[22:23], v[178:179] op_sel_hi:[1,0]
	v_pk_mul_f32 v[20:21], v[108:109], v[20:21]
	v_pk_mul_f32 v[22:23], v[110:111], v[22:23]
	v_pk_fma_f32 v[20:21], v[124:125], v[20:21], v[140:141]
	v_pk_fma_f32 v[22:23], v[126:127], v[22:23], v[142:143]
	v_cvt_pk_bf16_f32 v20, v20, v21
	v_cvt_pk_bf16_f32 v21, v22, v23
	global_store_dwordx2 v[182:183], v[20:21], off offset:1024
	v_pk_mul_f32 v[4:5], v[4:5], v[180:181] op_sel_hi:[1,0]
	v_pk_mul_f32 v[6:7], v[6:7], v[180:181] op_sel_hi:[1,0]
	v_pk_mul_f32 v[4:5], v[108:109], v[4:5]
	v_pk_mul_f32 v[6:7], v[110:111], v[6:7]
	v_pk_fma_f32 v[4:5], v[124:125], v[4:5], v[140:141]
	v_pk_fma_f32 v[6:7], v[126:127], v[6:7], v[142:143]
	v_cvt_pk_bf16_f32 v4, v4, v5
	v_cvt_pk_bf16_f32 v5, v6, v7
	global_store_dwordx2 v[184:185], v[4:5], off offset:1024
	v_pk_add_f32 v[128:129], v[128:129], 1.0 op_sel_hi:[1,0]
	v_pk_add_f32 v[130:131], v[130:131], 1.0 op_sel_hi:[1,0]
	v_pk_mul_f32 v[12:13], v[12:13], v[178:179] op_sel_hi:[1,0]
	v_pk_mul_f32 v[14:15], v[14:15], v[178:179] op_sel_hi:[1,0]
	v_pk_mul_f32 v[12:13], v[112:113], v[12:13]
	v_pk_mul_f32 v[14:15], v[114:115], v[14:15]
	v_pk_fma_f32 v[12:13], v[128:129], v[12:13], v[164:165]
	v_pk_fma_f32 v[14:15], v[130:131], v[14:15], v[166:167]
	v_cvt_pk_bf16_f32 v12, v12, v13
	v_cvt_pk_bf16_f32 v13, v14, v15
	global_store_dwordx2 v[182:183], v[12:13], off offset:1536
	v_pk_mul_f32 v[0:1], v[0:1], v[180:181] op_sel_hi:[1,0]
	v_pk_mul_f32 v[2:3], v[2:3], v[180:181] op_sel_hi:[1,0]
	v_pk_mul_f32 v[0:1], v[112:113], v[0:1]
	v_pk_mul_f32 v[2:3], v[114:115], v[2:3]
	v_pk_fma_f32 v[0:1], v[128:129], v[0:1], v[164:165]
	v_pk_fma_f32 v[2:3], v[130:131], v[2:3], v[166:167]
	v_cvt_pk_bf16_f32 v0, v0, v1
	v_cvt_pk_bf16_f32 v1, v2, v3
	global_store_dwordx2 v[184:185], v[0:1], off offset:1536
	v_readlane_b32 s2, v252, 2
	s_add_i32 s21, s21, s2
	v_readlane_b32 s2, v253, 43
	s_nop 1
	v_add_u32_e32 v36, s2, v36
	s_cmpk_lt_i32 s21, 0x1040
	s_cbranch_scc0 .LBB0_72

; DI void norm_phase(const float* lat, const float* ctxp, int nrows, const float* g, const float* modl, int shift_off, int scale_off,
;                    bf16_t* H, int bid, int nb) {
;     ...
;       const int row = r8 * 8 + wave + 4 * h;
;       const float* src = row < TL ? lat + (size_t)row * DM : ctxp + (size_t)(row - TL) * DM;
; #pragma unroll
;       for (int i = 0; i < 4; ++i) v[h][i] = *(const f32x4*)(src + lane * 4 + 256 * i);
;     }
; #pragma unroll
;     for (int h = 0; h < 2; ++h) {
; #pragma unroll
;       for (int i = 0; i < 4; ++i) ss[h] += v[h][i][0] * v[h][i][0] + v[h][i][1] * v[h][i][1] + v[h][i][2] * v[h][i][2] + v[h][i][3] * v[h][i][3];
;       ss[h] = wave_sum(ss[h]);
;     }
; #pragma unroll
;     for (int h = 0; h < 2; ++h) {
;       const int row = r8 * 8 + wave + 4 * h;
;       const int mi = row < TL ? (row >> 14) : 2;
;       const float* sh = modl + mi * 6144 + shift_off;
;       const float* sc = modl + mi * 6144 + scale_off;
;       const float rs = rsqrtf(ss[h] * (1.f / 1024.f) + EPS);
.LBB0_640:
	s_or_b64 exec, exec, s[2:3]
	v_lshl_add_u64 v[0:1], v[0:1], 0, v[192:193]
	global_load_dwordx4 v[16:19], v[0:1], off
	global_load_dwordx4 v[8:11], v[0:1], off offset:1024
	global_load_dwordx4 v[4:7], v[0:1], off offset:2048
	s_nop 0
	global_load_dwordx4 v[0:3], v[0:1], off offset:3072
	v_min_i32_e32 v168, 0x8000, v38
	v_readlane_b32 s28, v254, 46
	v_ashrrev_i32_e32 v168, 14, v168
	v_readlane_b32 s29, v254, 47
	v_mul_i32_i24_e32 v168, 0x1800, v168
	v_lshlrev_b64 v[182:183], 11, v[38:39]
	v_ashrrev_i32_e32 v169, 31, v168
	v_lshlrev_b64 v[184:185], 11, v[46:47]
	v_lshl_add_u64 v[170:171], v[168:169], 2, s[28:29]
	s_mov_b64 s[24:25], 0x3000
	s_mov_b64 s[26:27], 0x4000
	v_lshl_add_u64 v[172:173], v[170:171], 0, s[26:27]
	v_lshl_add_u64 v[170:171], v[170:171], 0, s[24:25]
	v_lshl_add_u64 v[170:171], v[170:171], 0, v[192:193]
	v_lshl_add_u64 v[172:173], v[172:173], 0, v[192:193]
	global_load_dwordx4 v[100:103], v[34:35], off
	global_load_dwordx4 v[116:119], v[172:173], off
	global_load_dwordx4 v[132:135], v[170:171], off
	global_load_dwordx4 v[104:107], v[34:35], off offset:1024
	global_load_dwordx4 v[120:123], v[172:173], off offset:1024
	global_load_dwordx4 v[136:139], v[170:171], off offset:1024
	global_load_dwordx4 v[108:111], v[34:35], off offset:2048
	global_load_dwordx4 v[124:127], v[172:173], off offset:2048
	global_load_dwordx4 v[140:143], v[170:171], off offset:2048
	global_load_dwordx4 v[112:115], v[34:35], off offset:3072
	global_load_dwordx4 v[128:131], v[172:173], off offset:3072
	global_load_dwordx4 v[164:167], v[170:171], off offset:3072
	v_lshl_add_u64 v[182:183], v[36:37], 0, v[182:183]
	v_lshl_add_u64 v[184:185], v[36:37], 0, v[184:185]
	s_waitcnt vmcnt(12)
	v_mul_f32_e32 v174, v28, v28
	v_fmac_f32_e32 v174, v29, v29
	v_fmac_f32_e32 v174, v30, v30
	v_fmac_f32_e32 v174, v31, v31
	v_fmac_f32_e32 v174, v24, v24
	v_fmac_f32_e32 v174, v25, v25
	v_fmac_f32_e32 v174, v26, v26
	v_fmac_f32_e32 v174, v27, v27
	v_fmac_f32_e32 v174, v20, v20
	v_fmac_f32_e32 v174, v21, v21
	v_fmac_f32_e32 v174, v22, v22
	v_fmac_f32_e32 v174, v23, v23
	v_fmac_f32_e32 v174, v12, v12
	v_fmac_f32_e32 v174, v13, v13
	v_fmac_f32_e32 v174, v14, v14
	v_fmac_f32_e32 v174, v15, v15
	v_mul_f32_e32 v175, v16, v16
	v_fmac_f32_e32 v175, v17, v17
	v_fmac_f32_e32 v175, v18, v18
	v_fmac_f32_e32 v175, v19, v19
	v_fmac_f32_e32 v175, v8, v8
	v_fmac_f32_e32 v175, v9, v9
	v_fmac_f32_e32 v175, v10, v10
	v_fmac_f32_e32 v175, v11, v11
	v_fmac_f32_e32 v175, v4, v4
	v_fmac_f32_e32 v175, v5, v5
	v_fmac_f32_e32 v175, v6, v6
	v_fmac_f32_e32 v175, v7, v7
	v_fmac_f32_e32 v175, v0, v0
	v_fmac_f32_e32 v175, v1, v1
	v_fmac_f32_e32 v175, v2, v2
	v_fmac_f32_e32 v175, v3, v3
	ds_bpermute_b32 v176, v33, v174
	ds_bpermute_b32 v177, v33, v175
	s_waitcnt lgkmcnt(0)
	v_add_f32_e32 v174, v174, v176
	v_add_f32_e32 v175, v175, v177
	ds_bpermute_b32 v176, v48, v174
	ds_bpermute_b32 v177, v48, v175
	s_waitcnt lgkmcnt(0)
	v_add_f32_e32 v174, v174, v176
	v_add_f32_e32 v175, v175, v177
	ds_bpermute_b32 v176, v49, v174
	ds_bpermute_b32 v177, v49, v175
	s_waitcnt lgkmcnt(0)
	v_add_f32_e32 v174, v174, v176
	v_add_f32_e32 v175, v175, v177
	ds_bpermute_b32 v176, v50, v174
	ds_bpermute_b32 v177, v50, v175
	s_waitcnt lgkmcnt(0)
	v_add_f32_e32 v174, v174, v176
	v_add_f32_e32 v175, v175, v177
	ds_bpermute_b32 v176, v51, v174
	ds_bpermute_b32 v177, v51, v175
	s_waitcnt lgkmcnt(0)
	v_add_f32_e32 v174, v174, v176
	v_add_f32_e32 v175, v175, v177
	ds_bpermute_b32 v176, v52, v174
	ds_bpermute_b32 v177, v52, v175
	s_waitcnt lgkmcnt(0)
	v_add_f32_e32 v174, v174, v176
	v_add_f32_e32 v175, v175, v177
	s_mov_b32 s2, 0x3a800000
	v_fma_f32 v174, v174, s2, v194
	v_fma_f32 v175, v175, s2, v194
	v_rsq_f32_e32 v178, v174
	v_rsq_f32_e32 v180, v175
	s_waitcnt vmcnt(0)
; DI unsigned pk2(float a, float b) { f32x2 v = {a, b}; return __builtin_bit_cast(unsigned, __builtin_convertvector(v, bf16x2_t)); }
; DI void norm_phase(const float* lat, const float* ctxp, int nrows, const float* g, const float* modl, int shift_off, int scale_off,
;                    bf16_t* H, int bid, int nb) {
;     ...
; #pragma unroll
;       for (int i = 0; i < 4; ++i) {
;         const int col = lane * 4 + 256 * i;
;         const f32x4 gg = *(const f32x4*)(g + col), s4 = *(const f32x4*)(sc + col), h4 = *(const f32x4*)(sh + col);
;         float y[4];
; #pragma unroll
;         for (int j = 0; j < 4; ++j) y[j] = (v[h][i][j] * rs * gg[j]) * (1.f + s4[j]) + h4[j];
;         u32x2 w; w[0] = pk2(y[0], y[1]); w[1] = pk2(y[2], y[3]);
;         *(u32x2*)(H + (size_t)row * DM + col) = w;
;       }
;     }
	v_pk_add_f32 v[116:117], v[116:117], 1.0 op_sel_hi:[1,0]
	v_pk_add_f32 v[118:119], v[118:119], 1.0 op_sel_hi:[1,0]
	v_pk_mul_f32 v[28:29], v[28:29], v[178:179] op_sel_hi:[1,0]
	v_pk_mul_f32 v[30:31], v[30:31], v[178:179] op_sel_hi:[1,0]
	v_pk_mul_f32 v[28:29], v[100:101], v[28:29]
	v_pk_mul_f32 v[30:31], v[102:103], v[30:31]
	v_pk_fma_f32 v[28:29], v[116:117], v[28:29], v[132:133]
	v_pk_fma_f32 v[30:31], v[118:119], v[30:31], v[134:135]
	v_cvt_pk_bf16_f32 v28, v28, v29
	v_cvt_pk_bf16_f32 v29, v30, v31
	global_store_dwordx2 v[182:183], v[28:29], off
	v_pk_mul_f32 v[16:17], v[16:17], v[180:181] op_sel_hi:[1,0]
	v_pk_mul_f32 v[18:19], v[18:19], v[180:181] op_sel_hi:[1,0]
	v_pk_mul_f32 v[16:17], v[100:101], v[16:17]
	v_pk_mul_f32 v[18:19], v[102:103], v[18:19]
	v_pk_fma_f32 v[16:17], v[116:117], v[16:17], v[132:133]
	v_pk_fma_f32 v[18:19], v[118:119], v[18:19], v[134:135]
	v_cvt_pk_bf16_f32 v16, v16, v17
	v_cvt_pk_bf16_f32 v17, v18, v19
	global_store_dwordx2 v[184:185], v[16:17], off
	v_pk_add_f32 v[120:121], v[120:121], 1.0 op_sel_hi:[1,0]
	v_pk_add_f32 v[122:123], v[122:123], 1.0 op_sel_hi:[1,0]
	v_pk_mul_f32 v[24:25], v[24:25], v[178:179] op_sel_hi:[1,0]
	v_pk_mul_f32 v[26:27], v[26:27], v[178:179] op_sel_hi:[1,0]
	v_pk_mul_f32 v[24:25], v[104:105], v[24:25]
	v_pk_mul_f32 v[26:27], v[106:107], v[26:27]
	v_pk_fma_f32 v[24:25], v[120:121], v[24:25], v[136:137]
	v_pk_fma_f32 v[26:27], v[122:123], v[26:27], v[138:139]
	v_cvt_pk_bf16_f32 v24, v24, v25
	v_cvt_pk_bf16_f32 v25, v26, v27
	global_store_dwordx2 v[182:183], v[24:25], off offset:512
	v_pk_mul_f32 v[8:9], v[8:9], v[180:181] op_sel_hi:[1,0]
	v_pk_mul_f32 v[10:11], v[10:11], v[180:181] op_sel_hi:[1,0]
	v_pk_mul_f32 v[8:9], v[104:105], v[8:9]
	v_pk_mul_f32 v[10:11], v[106:107], v[10:11]
	v_pk_fma_f32 v[8:9], v[120:121], v[8:9], v[136:137]
	v_pk_fma_f32 v[10:11], v[122:123], v[10:11], v[138:139]
	v_cvt_pk_bf16_f32 v8, v8, v9
	v_cvt_pk_bf16_f32 v9, v10, v11
	global_store_dwordx2 v[184:185], v[8:9], off offset:512
	v_pk_add_f32 v[124:125], v[124:125], 1.0 op_sel_hi:[1,0]
	v_pk_add_f32 v[126:127], v[126:127], 1.0 op_sel_hi:[1,0]
	v_pk_mul_f32 v[20:21], v[20:21], v[178:179] op_sel_hi:[1,0]
	v_pk_mul_f32 v[22:23], v[22:23], v[178:179] op_sel_hi:[1,0]
	v_pk_mul_f32 v[20:21], v[108:109], v[20:21]
	v_pk_mul_f32 v[22:23], v[110:111], v[22:23]
	v_pk_fma_f32 v[20:21], v[124:125], v[20:21], v[140:141]
	v_pk_fma_f32 v[22:23], v[126:127], v[22:23], v[142:143]
	v_cvt_pk_bf16_f32 v20, v20, v21
	v_cvt_pk_bf16_f32 v21, v22, v23
	global_store_dwordx2 v[182:183], v[20:21], off offset:1024
	v_pk_mul_f32 v[4:5], v[4:5], v[180:181] op_sel_hi:[1,0]
	v_pk_mul_f32 v[6:7], v[6:7], v[180:181] op_sel_hi:[1,0]
	v_pk_mul_f32 v[4:5], v[108:109], v[4:5]
	v_pk_mul_f32 v[6:7], v[110:111], v[6:7]
	v_pk_fma_f32 v[4:5], v[124:125], v[4:5], v[140:141]
	v_pk_fma_f32 v[6:7], v[126:127], v[6:7], v[142:143]
	v_cvt_pk_bf16_f32 v4, v4, v5
	v_cvt_pk_bf16_f32 v5, v6, v7
	global_store_dwordx2 v[184:185], v[4:5], off offset:1024
	v_pk_add_f32 v[128:129], v[128:129], 1.0 op_sel_hi:[1,0]
	v_pk_add_f32 v[130:131], v[130:131], 1.0 op_sel_hi:[1,0]
	v_pk_mul_f32 v[12:13], v[12:13], v[178:179] op_sel_hi:[1,0]
	v_pk_mul_f32 v[14:15], v[14:15], v[178:179] op_sel_hi:[1,0]
	v_pk_mul_f32 v[12:13], v[112:113], v[12:13]
	v_pk_mul_f32 v[14:15], v[114:115], v[14:15]
	v_pk_fma_f32 v[12:13], v[128:129], v[12:13], v[164:165]
	v_pk_fma_f32 v[14:15], v[130:131], v[14:15], v[166:167]
	v_cvt_pk_bf16_f32 v12, v12, v13
	v_cvt_pk_bf16_f32 v13, v14, v15
	global_store_dwordx2 v[182:183], v[12:13], off offset:1536
	v_pk_mul_f32 v[0:1], v[0:1], v[180:181] op_sel_hi:[1,0]
	v_pk_mul_f32 v[2:3], v[2:3], v[180:181] op_sel_hi:[1,0]
	v_pk_mul_f32 v[0:1], v[112:113], v[0:1]
	v_pk_mul_f32 v[2:3], v[114:115], v[2:3]
	v_pk_fma_f32 v[0:1], v[128:129], v[0:1], v[164:165]
	v_pk_fma_f32 v[2:3], v[130:131], v[2:3], v[166:167]
	v_cvt_pk_bf16_f32 v0, v0, v1
	v_cvt_pk_bf16_f32 v1, v2, v3
	global_store_dwordx2 v[184:185], v[0:1], off offset:1536
	v_readlane_b32 s2, v252, 2
	s_add_i32 s22, s22, s2
	v_readlane_b32 s2, v253, 43
	s_nop 1
	v_add_u32_e32 v38, s2, v38
	s_cmp_lt_i32 s22, s21
	s_cbranch_scc0 .LBB0_645
